# rwkv post-processing of the prompt rows fused into the scan/attention phase (waves 5-7, per-sequence progress words, XCC-local scan unit groups); post phase keeps sample rows
# speedup vs baseline: 1.0925x; 1.0052x over previous
.LBB0_448:
	s_or_b64 exec, exec, s[0:1]
	v_add_u32_e32 v26, 0x2000, v26
	s_movk_i32 s0, 0x2080
	v_cmp_gt_i32_e32 vcc, s0, v26
	s_and_saveexec_b64 s[38:39], vcc
	v_readlane_b32 s12, v253, 52
	v_readlane_b32 s42, v253, 54
	v_readlane_b32 s44, v253, 56
	v_readlane_b32 s13, v253, 53
	v_readlane_b32 s43, v253, 55
	v_readlane_b32 s45, v253, 57
	s_movk_i32 s36, 0x207f
	s_cbranch_execz .LBB0_451
	v_and_b32_e32 v2, 64, v163
	v_xor_b32_e32 v0, 1, v163
	v_add_u32_e32 v2, 64, v2
	v_cmp_lt_i32_e32 vcc, v0, v2
	v_ashrrev_i32_e32 v27, 31, v26
	v_readlane_b32 s72, v254, 45
	v_cndmask_b32_e32 v0, v163, v0, vcc
	v_lshlrev_b32_e32 v80, 2, v0
	v_xor_b32_e32 v0, 2, v163
	v_cmp_lt_i32_e32 vcc, v0, v2
	s_mov_b64 s[0:1], 0x4f90000
	v_readlane_b32 s76, v254, 49
	v_cndmask_b32_e32 v0, v163, v0, vcc
	v_lshlrev_b32_e32 v81, 2, v0
	v_xor_b32_e32 v0, 4, v163
	v_cmp_lt_i32_e32 vcc, v0, v2
	v_lshlrev_b64 v[2:3], 6, v[26:27]
	v_readlane_b32 s77, v254, 50
	v_cndmask_b32_e32 v0, v163, v0, vcc
	v_lshlrev_b32_e32 v82, 2, v0
	v_lshlrev_b32_e32 v0, 5, v24
	v_readlane_b32 s78, v254, 51
	v_readlane_b32 s79, v254, 52
	v_lshl_add_u64 v[36:37], v[2:3], 0, s[0:1]
	v_lshrrev_b32_e32 v2, 1, v24
	v_lshl_add_u64 v[28:29], s[76:77], 0, v[0:1]
	v_lshl_add_u64 v[30:31], s[78:79], 0, v[0:1]
	v_lshlrev_b64 v[32:33], 12, v[26:27]
	v_lshlrev_b32_e32 v0, 4, v24
	v_and_or_b32 v36, v2, 28, v36
	v_lshlrev_b64 v[40:41], 11, v[26:27]
	v_or_b32_e32 v34, v32, v0
	v_mov_b32_e32 v35, v33
	v_or_b32_e32 v38, 32, v36
	v_mov_b32_e32 v39, v37
	v_or_b32_e32 v40, v40, v0
	v_lshl_or_b32 v32, v24, 5, v32
	s_mov_b64 s[40:41], 0
	v_readlane_b32 s73, v254, 46
	v_readlane_b32 s74, v254, 47
	v_readlane_b32 s75, v254, 48
	v_readlane_b32 s80, v254, 53
	v_readlane_b32 s81, v254, 54
	v_readlane_b32 s82, v254, 55
	v_readlane_b32 s83, v254, 56
	v_readlane_b32 s84, v254, 57
	v_readlane_b32 s85, v254, 58
	v_readlane_b32 s86, v254, 59
	v_readlane_b32 s87, v254, 60

.LBB0_452:
	s_and_b64 vcc, exec, s[0:1]
	s_cbranch_vccz .LBB0_552
	v_readfirstlane_b32 s12, v166
	v_cmp_gt_i32_e32 vcc, 12, v166
	s_waitcnt vmcnt(0) lgkmcnt(0)
	s_barrier
	s_and_saveexec_b64 s[0:1], vcc
	v_lshl_add_u32 v0, v166, 2, 0
	v_add_u32_e32 v0, 0x15000, v0
	ds_write_b32 v0, v1
	s_or_b64 exec, exec, s[0:1]
	v_cmp_eq_u32_e32 vcc, 0, v166
	s_and_saveexec_b64 s[0:1], vcc
	s_cbranch_execz .Lxu_skip
	s_getreg_b32 s13, hwreg(HW_REG_XCC_ID, 0, 4)
	s_lshl_b32 s36, s13, 2
	s_add_u32 s38, s24, 0x5016000
	s_addc_u32 s39, s25, 0
	v_mov_b32_e32 v2, s36
	v_mov_b32_e32 v3, 1
	global_atomic_add v3, v2, v3, s[38:39] sc0
	s_waitcnt vmcnt(0)
	v_lshl_add_u32 v3, s13, 5, v3
	v_mov_b32_e32 v2, 0x15030
	ds_write_b32 v2, v3
.Lxu_skip:
	s_or_b64 exec, exec, s[0:1]
	s_ashr_i32 s82, s12, 6
	s_cmp_lt_i32 s82, 4
	s_cselect_b64 s[0:1], -1, 0
	s_cmp_gt_i32 s82, 4
	s_waitcnt lgkmcnt(0)
	s_barrier
	s_cbranch_scc1 .LBB0_457
	s_setprio 3
.LBB0_457:
	s_cmp_gt_i32 s82, 4
	v_and_b32_e32 v161, 63, v166
	s_cbranch_scc1 .LBB0_519
	v_writelane_b32 v255, s0, 39
	s_mov_b32 s96, s88
	s_nop 0
	v_writelane_b32 v255, s1, 40
	v_readlane_b32 s0, v250, 34
	v_readlane_b32 s1, v250, 35
	s_andn2_b64 vcc, exec, s[0:1]
	s_cbranch_vccnz .LBB0_512
	v_lshlrev_b32_e32 v0, 4, v161
	v_readlane_b32 s0, v255, 35
	v_and_b32_e32 v170, 0xf0, v0
	v_mov_b32_e32 v171, v1
	v_readlane_b32 s1, v255, 36
	v_and_b32_e32 v0, 0x1f0, v0
	v_and_b32_e32 v2, 1, v166
	v_lshl_add_u64 v[172:173], s[0:1], 0, v[170:171]
	v_readlane_b32 s0, v255, 33
	v_readlane_b32 s1, v255, 34
	v_lshlrev_b32_e32 v187, 5, v2
	v_lshrrev_b32_e32 v191, 5, v161
	v_lshl_add_u64 v[174:175], s[0:1], 0, v[0:1]
	v_lshlrev_b32_e32 v0, 3, v2
	v_or_b32_e32 v2, 64, v161
	v_lshrrev_b32_e32 v188, 4, v2
	v_lshrrev_b32_e32 v192, 5, v2
	s_movk_i32 s0, 0x500
	v_mov_b32_e32 v2, 0x2800
	v_mad_u32_u24 v229, v191, s0, v2
	v_mov_b32_e32 v2, 0x3200
	v_lshlrev_b32_e32 v3, 5, v161
	v_mad_u32_u24 v230, v191, s0, v2
	v_mov_b32_e32 v2, 0x3c00
	v_lshrrev_b32_e32 v167, 4, v161
	v_and_b32_e32 v185, 0x3e0, v3
	v_and_b32_e32 v186, 0x3c0, v3
	v_or_b32_e32 v3, 0x80, v161
	v_or_b32_e32 v4, 0xc0, v161
	v_mad_u32_u24 v231, v191, s0, v2
	v_mov_b32_e32 v2, 0x4600
	s_cmp_lt_i32 s82, 4
	v_lshl_or_b32 v169, s82, 2, v167
	v_and_b32_e32 v182, 15, v166
	v_lshrrev_b32_e32 v189, 4, v3
	v_lshrrev_b32_e32 v190, 4, v4
	v_lshrrev_b32_e32 v193, 5, v3
	v_lshrrev_b32_e32 v194, 5, v4
	v_mad_u32_u24 v232, v191, s0, v2
	v_readlane_b32 s0, v255, 13
	s_cselect_b64 s[42:43], -1, 0
	v_lshlrev_b32_e32 v168, 2, v182
	v_lshlrev_b32_e32 v183, 4, v182
	v_lshlrev_b32_e32 v184, 2, v169
	s_mov_b32 s83, 0
	v_cmp_eq_u32_e64 s[38:39], 0, v161
	v_bfe_u32 v171, v166, 1, 4
	v_cmp_gt_u32_e64 s[44:45], 32, v161
	v_cmp_eq_u32_e64 s[8:9], 0, v182
	v_cmp_eq_u32_e64 s[10:11], 1, v182
	v_cmp_eq_u32_e64 s[18:19], 2, v182
	v_cmp_eq_u32_e64 s[6:7], 3, v182
	v_cmp_eq_u32_e64 s[80:81], 4, v182
	v_cmp_eq_u32_e64 s[90:91], 5, v182
	v_cmp_eq_u32_e64 s[74:75], 6, v182
	v_cmp_eq_u32_e64 s[56:57], 7, v182
	v_cmp_eq_u32_e64 s[58:59], 8, v182
	v_cmp_eq_u32_e64 s[60:61], 9, v182
	v_cmp_eq_u32_e64 s[62:63], 10, v182
	v_cmp_eq_u32_e64 s[64:65], 11, v182
	v_cmp_eq_u32_e64 s[66:67], 12, v182
	v_cmp_eq_u32_e64 s[68:69], 14, v182
	v_cmp_eq_u32_e64 s[70:71], 13, v182
	v_cmp_eq_u32_e64 s[72:73], 15, v182
	v_or_b32_e32 v195, 8, v191
	v_or_b32_e32 v196, 10, v191
	v_or_b32_e32 v197, 12, v191
	v_or_b32_e32 v198, 14, v191
	v_mul_u32_u24_e32 v199, 0x500, v167
	v_mul_u32_u24_e32 v200, 0x500, v188
	v_mul_u32_u24_e32 v201, 0x500, v189
	v_mul_u32_u24_e32 v224, 0x500, v190
	v_mul_u32_u24_e32 v225, 0x500, v191
	v_mul_u32_u24_e32 v226, 0x500, v192
	v_mul_u32_u24_e32 v227, 0x500, v193
	v_mul_u32_u24_e32 v228, 0x500, v194
	v_lshlrev_b32_e32 v0, 1, v0
	v_mov_b32_e32 v2, 0x15030
	ds_read_b32 v2, v2
	s_waitcnt lgkmcnt(0)
	v_readfirstlane_b32 s84, v2
	v_readlane_b32 s1, v255, 14
	s_branch .LBB0_462

.LBB0_472:
	s_mov_b32 s78, 0xcccccccc
	s_mov_b32 s79, 0xcccccccc
	s_mov_b32 s96, 0xaaaaaaaa
	s_mov_b32 s97, 0xaaaaaaaa
	s_add_i32 s77, s36, s83
	s_and_b32 s86, s77, 3
	s_mul_i32 s12, s86, 0x5400
	s_lshl_b32 s86, s86, 2
	s_add_i32 s77, s77, 1
	v_add_u32_e32 v32, s12, v183
	v_add_u32_e32 v33, s12, v184
	v_add_u32_e32 v33, 0x5000, v33
	s_add_u32 s98, s24, 0x4a80000
	s_addc_u32 s99, s25, 0
	s_lshl_b32 s12, s84, 4
	s_lshl_b32 s13, s82, 2
	s_add_i32 s12, s12, s13
	v_mov_b32_e32 v29, s12

.Lsc_chunk:
	s_waitcnt lgkmcnt(5)
	v_pk_mul_f32 v[156:157], v[54:55], v[80:81]
	v_pk_fma_f32 v[156:157], v[56:57], v[82:83], v[156:157]
	v_add_f32_e32 v2, v156, v157
	ds_read_b128 v[120:123], v32 offset:3328
	ds_read_b128 v[116:119], v32 offset:3072
	v_add_f32_dpp v2, v2, v2 row_ror:8 row_mask:0xf bank_mask:0xf bound_ctrl:1
	ds_read2_b32 v[150:151], v33 offset0:32 offset1:48
	v_pk_mul_f32 v[4:5], v[76:77], v[148:149] op_sel_hi:[1,0]
	v_add_f32_dpp v2, v2, v2 row_ror:4 row_mask:0xf bank_mask:0xf bound_ctrl:1
	v_pk_mul_f32 v[6:7], v[78:79], v[148:149] op_sel_hi:[1,0]
	v_pk_fma_f32 v[4:5], v[54:55], v[68:69], v[4:5]
	v_add_f32_dpp v2, v2, v2 row_ror:2 row_mask:0xf bank_mask:0xf bound_ctrl:1
	v_pk_fma_f32 v[6:7], v[56:57], v[70:71], v[6:7]
	ds_read_b128 v[108:111], v32 offset:2560
	v_add_f32_dpp v2, v2, v2 row_ror:1 row_mask:0xf bank_mask:0xf bound_ctrl:1
	v_pk_fma_f32 v[54:55], v[84:85], v[2:3], v[4:5] op_sel_hi:[1,0,1] neg_lo:[1,0,0] neg_hi:[1,0,0]
	v_pk_fma_f32 v[56:57], v[86:87], v[2:3], v[6:7] op_sel_hi:[1,0,1] neg_lo:[1,0,0] neg_hi:[1,0,0]
	ds_read_b128 v[124:127], v32 offset:3584
	ds_read_b128 v[112:115], v32 offset:2816
	s_waitcnt lgkmcnt(6)
	v_pk_mul_f32 v[156:157], v[54:55], v[100:101]
	v_pk_fma_f32 v[156:157], v[56:57], v[102:103], v[156:157]
	v_add_f32_e32 v2, v156, v157
	v_pk_mul_f32 v[8:9], v[54:55], v[72:73]
	v_pk_fma_f32 v[8:9], v[56:57], v[74:75], v[8:9]
	v_add_f32_dpp v2, v2, v2 row_ror:8 row_mask:0xf bank_mask:0xf bound_ctrl:1
	v_add_f32_e32 v66, v8, v9
	v_pk_mul_f32 v[4:5], v[96:97], v[148:149] op_sel:[0,1] op_sel_hi:[1,1]
	v_add_f32_dpp v2, v2, v2 row_ror:4 row_mask:0xf bank_mask:0xf bound_ctrl:1
	v_pk_mul_f32 v[6:7], v[98:99], v[148:149] op_sel:[0,1] op_sel_hi:[1,1]
	v_pk_fma_f32 v[4:5], v[54:55], v[88:89], v[4:5]
	v_add_f32_dpp v2, v2, v2 row_ror:2 row_mask:0xf bank_mask:0xf bound_ctrl:1
	v_pk_fma_f32 v[6:7], v[56:57], v[90:91], v[6:7]
	ds_read_b128 v[140:143], v32 offset:4608
	v_add_f32_dpp v2, v2, v2 row_ror:1 row_mask:0xf bank_mask:0xf bound_ctrl:1
	v_pk_fma_f32 v[54:55], v[104:105], v[2:3], v[4:5] op_sel_hi:[1,0,1] neg_lo:[1,0,0] neg_hi:[1,0,0]
	v_pk_fma_f32 v[56:57], v[106:107], v[2:3], v[6:7] op_sel_hi:[1,0,1] neg_lo:[1,0,0] neg_hi:[1,0,0]
	ds_read_b128 v[136:139], v32 offset:4352
	ds_read_b128 v[128:131], v32 offset:3840
	ds_read_b128 v[144:147], v32 offset:4864
	ds_read_b128 v[132:135], v32 offset:4096
	s_waitcnt lgkmcnt(5)
	v_pk_mul_f32 v[156:157], v[54:55], v[120:121]
	v_pk_fma_f32 v[156:157], v[56:57], v[122:123], v[156:157]
	v_add_f32_e32 v2, v156, v157
	v_pk_mul_f32 v[8:9], v[54:55], v[92:93]
	v_pk_fma_f32 v[8:9], v[56:57], v[94:95], v[8:9]
	v_add_f32_dpp v2, v2, v2 row_ror:8 row_mask:0xf bank_mask:0xf bound_ctrl:1
	v_add_f32_e32 v10, v8, v9
	v_pk_mul_f32 v[4:5], v[116:117], v[150:151] op_sel_hi:[1,0]
	v_add_f32_dpp v2, v2, v2 row_ror:4 row_mask:0xf bank_mask:0xf bound_ctrl:1
	v_pk_mul_f32 v[6:7], v[118:119], v[150:151] op_sel_hi:[1,0]
	v_pk_fma_f32 v[4:5], v[54:55], v[108:109], v[4:5]
	v_add_f32_dpp v2, v2, v2 row_ror:2 row_mask:0xf bank_mask:0xf bound_ctrl:1
	v_pk_fma_f32 v[6:7], v[56:57], v[110:111], v[6:7]
	ds_read_b128 v[80:83], v32 offset:5888
	v_add_f32_dpp v2, v2, v2 row_ror:1 row_mask:0xf bank_mask:0xf bound_ctrl:1
	v_pk_fma_f32 v[54:55], v[124:125], v[2:3], v[4:5] op_sel_hi:[1,0,1] neg_lo:[1,0,0] neg_hi:[1,0,0]
	v_pk_fma_f32 v[56:57], v[126:127], v[2:3], v[6:7] op_sel_hi:[1,0,1] neg_lo:[1,0,0] neg_hi:[1,0,0]
	ds_read_b128 v[76:79], v32 offset:5632
	ds_read2_b32 v[152:153], v33 offset0:64 offset1:80
	ds_read_b128 v[68:71], v32 offset:5120
	ds_read_b128 v[84:87], v32 offset:6144
	ds_read_b128 v[72:75], v32 offset:5376
	s_waitcnt lgkmcnt(6)
	v_pk_mul_f32 v[156:157], v[54:55], v[140:141]
	v_pk_fma_f32 v[156:157], v[56:57], v[142:143], v[156:157]
	v_add_f32_e32 v2, v156, v157
	v_pk_mul_f32 v[8:9], v[54:55], v[112:113]
	v_pk_fma_f32 v[8:9], v[56:57], v[114:115], v[8:9]
	v_add_f32_dpp v2, v2, v2 row_ror:8 row_mask:0xf bank_mask:0xf bound_ctrl:1
	v_add_f32_e32 v11, v8, v9
	v_pk_mul_f32 v[4:5], v[136:137], v[150:151] op_sel:[0,1] op_sel_hi:[1,1]
	v_add_f32_dpp v2, v2, v2 row_ror:4 row_mask:0xf bank_mask:0xf bound_ctrl:1
	v_pk_mul_f32 v[6:7], v[138:139], v[150:151] op_sel:[0,1] op_sel_hi:[1,1]
	v_pk_fma_f32 v[4:5], v[54:55], v[128:129], v[4:5]
	v_add_f32_dpp v2, v2, v2 row_ror:2 row_mask:0xf bank_mask:0xf bound_ctrl:1
	v_pk_fma_f32 v[6:7], v[56:57], v[130:131], v[6:7]
	ds_read_b128 v[100:103], v32 offset:7168
	v_add_f32_dpp v2, v2, v2 row_ror:1 row_mask:0xf bank_mask:0xf bound_ctrl:1
	v_pk_fma_f32 v[54:55], v[144:145], v[2:3], v[4:5] op_sel_hi:[1,0,1] neg_lo:[1,0,0] neg_hi:[1,0,0]
	v_pk_fma_f32 v[56:57], v[146:147], v[2:3], v[6:7] op_sel_hi:[1,0,1] neg_lo:[1,0,0] neg_hi:[1,0,0]
	ds_read_b128 v[96:99], v32 offset:6912
	ds_read_b128 v[88:91], v32 offset:6400
	ds_read_b128 v[104:107], v32 offset:7424
	ds_read_b128 v[92:95], v32 offset:6656
	s_waitcnt lgkmcnt(5)
	v_pk_mul_f32 v[156:157], v[54:55], v[80:81]
	v_pk_fma_f32 v[156:157], v[56:57], v[82:83], v[156:157]
	v_add_f32_e32 v2, v156, v157
	v_pk_mul_f32 v[8:9], v[54:55], v[132:133]
	v_pk_fma_f32 v[8:9], v[56:57], v[134:135], v[8:9]
	v_add_f32_dpp v2, v2, v2 row_ror:8 row_mask:0xf bank_mask:0xf bound_ctrl:1
	v_add_f32_e32 v12, v8, v9
	v_pk_mul_f32 v[4:5], v[76:77], v[152:153] op_sel_hi:[1,0]
	v_add_f32_dpp v2, v2, v2 row_ror:4 row_mask:0xf bank_mask:0xf bound_ctrl:1
	v_pk_mul_f32 v[6:7], v[78:79], v[152:153] op_sel_hi:[1,0]
	v_pk_fma_f32 v[4:5], v[54:55], v[68:69], v[4:5]
	v_add_f32_dpp v2, v2, v2 row_ror:2 row_mask:0xf bank_mask:0xf bound_ctrl:1
	v_pk_fma_f32 v[6:7], v[56:57], v[70:71], v[6:7]
	ds_read_b128 v[120:123], v32 offset:8448
	v_add_f32_dpp v2, v2, v2 row_ror:1 row_mask:0xf bank_mask:0xf bound_ctrl:1
	v_pk_fma_f32 v[54:55], v[84:85], v[2:3], v[4:5] op_sel_hi:[1,0,1] neg_lo:[1,0,0] neg_hi:[1,0,0]
	v_pk_fma_f32 v[56:57], v[86:87], v[2:3], v[6:7] op_sel_hi:[1,0,1] neg_lo:[1,0,0] neg_hi:[1,0,0]
	ds_read_b128 v[116:119], v32 offset:8192
	ds_read2_b32 v[154:155], v33 offset0:96 offset1:112
	ds_read_b128 v[108:111], v32 offset:7680
	ds_read_b128 v[124:127], v32 offset:8704
	ds_read_b128 v[112:115], v32 offset:7936
	s_waitcnt lgkmcnt(6)
	v_pk_mul_f32 v[156:157], v[54:55], v[100:101]
	v_pk_fma_f32 v[156:157], v[56:57], v[102:103], v[156:157]
	v_add_f32_e32 v2, v156, v157
	v_pk_mul_f32 v[8:9], v[54:55], v[72:73]
	v_pk_fma_f32 v[8:9], v[56:57], v[74:75], v[8:9]
	v_add_f32_dpp v2, v2, v2 row_ror:8 row_mask:0xf bank_mask:0xf bound_ctrl:1
	v_add_f32_e32 v13, v8, v9
	v_pk_mul_f32 v[4:5], v[96:97], v[152:153] op_sel:[0,1] op_sel_hi:[1,1]
	v_add_f32_dpp v2, v2, v2 row_ror:4 row_mask:0xf bank_mask:0xf bound_ctrl:1
	v_pk_mul_f32 v[6:7], v[98:99], v[152:153] op_sel:[0,1] op_sel_hi:[1,1]
	v_pk_fma_f32 v[4:5], v[54:55], v[88:89], v[4:5]
	v_add_f32_dpp v2, v2, v2 row_ror:2 row_mask:0xf bank_mask:0xf bound_ctrl:1
	v_pk_fma_f32 v[6:7], v[56:57], v[90:91], v[6:7]
	ds_read_b128 v[140:143], v32 offset:9728
	v_add_f32_dpp v2, v2, v2 row_ror:1 row_mask:0xf bank_mask:0xf bound_ctrl:1
	v_pk_fma_f32 v[54:55], v[104:105], v[2:3], v[4:5] op_sel_hi:[1,0,1] neg_lo:[1,0,0] neg_hi:[1,0,0]
	v_pk_fma_f32 v[56:57], v[106:107], v[2:3], v[6:7] op_sel_hi:[1,0,1] neg_lo:[1,0,0] neg_hi:[1,0,0]
	ds_read_b128 v[136:139], v32 offset:9472
	ds_read_b128 v[128:131], v32 offset:8960
	ds_read_b128 v[144:147], v32 offset:9984
	ds_read_b128 v[132:135], v32 offset:9216
	s_waitcnt lgkmcnt(5)
	v_pk_mul_f32 v[156:157], v[54:55], v[120:121]
	v_pk_fma_f32 v[156:157], v[56:57], v[122:123], v[156:157]
	v_add_f32_e32 v2, v156, v157
	v_pk_mul_f32 v[8:9], v[54:55], v[92:93]
	v_pk_fma_f32 v[8:9], v[56:57], v[94:95], v[8:9]
	v_add_f32_dpp v2, v2, v2 row_ror:8 row_mask:0xf bank_mask:0xf bound_ctrl:1
	v_add_f32_e32 v14, v8, v9
	v_pk_mul_f32 v[4:5], v[116:117], v[154:155] op_sel_hi:[1,0]
	v_add_f32_dpp v2, v2, v2 row_ror:4 row_mask:0xf bank_mask:0xf bound_ctrl:1
	v_pk_mul_f32 v[6:7], v[118:119], v[154:155] op_sel_hi:[1,0]
	v_pk_fma_f32 v[4:5], v[54:55], v[108:109], v[4:5]
	v_add_f32_dpp v2, v2, v2 row_ror:2 row_mask:0xf bank_mask:0xf bound_ctrl:1
	v_pk_fma_f32 v[6:7], v[56:57], v[110:111], v[6:7]
	ds_read_b128 v[80:83], v32 offset:11008
	v_add_f32_dpp v2, v2, v2 row_ror:1 row_mask:0xf bank_mask:0xf bound_ctrl:1
	v_pk_fma_f32 v[54:55], v[124:125], v[2:3], v[4:5] op_sel_hi:[1,0,1] neg_lo:[1,0,0] neg_hi:[1,0,0]
	v_pk_fma_f32 v[56:57], v[126:127], v[2:3], v[6:7] op_sel_hi:[1,0,1] neg_lo:[1,0,0] neg_hi:[1,0,0]
	ds_read_b128 v[76:79], v32 offset:10752
	ds_read2_b32 v[148:149], v33 offset0:128 offset1:144
	ds_read_b128 v[68:71], v32 offset:10240
	ds_read_b128 v[84:87], v32 offset:11264
	ds_read_b128 v[72:75], v32 offset:10496
	s_waitcnt lgkmcnt(6)
	v_pk_mul_f32 v[156:157], v[54:55], v[140:141]
	v_pk_fma_f32 v[156:157], v[56:57], v[142:143], v[156:157]
	v_add_f32_e32 v2, v156, v157
	v_pk_mul_f32 v[8:9], v[54:55], v[112:113]
	v_pk_fma_f32 v[8:9], v[56:57], v[114:115], v[8:9]
	v_add_f32_dpp v2, v2, v2 row_ror:8 row_mask:0xf bank_mask:0xf bound_ctrl:1
	v_add_f32_e32 v15, v8, v9
	v_pk_mul_f32 v[4:5], v[136:137], v[154:155] op_sel:[0,1] op_sel_hi:[1,1]
	v_add_f32_dpp v2, v2, v2 row_ror:4 row_mask:0xf bank_mask:0xf bound_ctrl:1
	v_pk_mul_f32 v[6:7], v[138:139], v[154:155] op_sel:[0,1] op_sel_hi:[1,1]
	v_pk_fma_f32 v[4:5], v[54:55], v[128:129], v[4:5]
	v_add_f32_dpp v2, v2, v2 row_ror:2 row_mask:0xf bank_mask:0xf bound_ctrl:1
	v_pk_fma_f32 v[6:7], v[56:57], v[130:131], v[6:7]
	ds_read_b128 v[100:103], v32 offset:12288
	v_add_f32_dpp v2, v2, v2 row_ror:1 row_mask:0xf bank_mask:0xf bound_ctrl:1
	v_pk_fma_f32 v[54:55], v[144:145], v[2:3], v[4:5] op_sel_hi:[1,0,1] neg_lo:[1,0,0] neg_hi:[1,0,0]
	v_pk_fma_f32 v[56:57], v[146:147], v[2:3], v[6:7] op_sel_hi:[1,0,1] neg_lo:[1,0,0] neg_hi:[1,0,0]
	ds_read_b128 v[96:99], v32 offset:12032
	ds_read_b128 v[88:91], v32 offset:11520
	ds_read_b128 v[104:107], v32 offset:12544
	ds_read_b128 v[92:95], v32 offset:11776
	s_waitcnt lgkmcnt(5)
	v_pk_mul_f32 v[156:157], v[54:55], v[80:81]
	v_pk_fma_f32 v[156:157], v[56:57], v[82:83], v[156:157]
	v_add_f32_e32 v2, v156, v157
	v_pk_mul_f32 v[8:9], v[54:55], v[132:133]
	v_pk_fma_f32 v[8:9], v[56:57], v[134:135], v[8:9]
	v_add_f32_dpp v2, v2, v2 row_ror:8 row_mask:0xf bank_mask:0xf bound_ctrl:1
	v_add_f32_e32 v16, v8, v9
	v_pk_mul_f32 v[4:5], v[76:77], v[148:149] op_sel_hi:[1,0]
	v_add_f32_dpp v2, v2, v2 row_ror:4 row_mask:0xf bank_mask:0xf bound_ctrl:1
	v_pk_mul_f32 v[6:7], v[78:79], v[148:149] op_sel_hi:[1,0]
	v_pk_fma_f32 v[4:5], v[54:55], v[68:69], v[4:5]
	v_add_f32_dpp v2, v2, v2 row_ror:2 row_mask:0xf bank_mask:0xf bound_ctrl:1
	v_pk_fma_f32 v[6:7], v[56:57], v[70:71], v[6:7]
	ds_read_b128 v[120:123], v32 offset:13568
	v_add_f32_dpp v2, v2, v2 row_ror:1 row_mask:0xf bank_mask:0xf bound_ctrl:1
	v_pk_fma_f32 v[54:55], v[84:85], v[2:3], v[4:5] op_sel_hi:[1,0,1] neg_lo:[1,0,0] neg_hi:[1,0,0]
	v_pk_fma_f32 v[56:57], v[86:87], v[2:3], v[6:7] op_sel_hi:[1,0,1] neg_lo:[1,0,0] neg_hi:[1,0,0]
	ds_read_b128 v[116:119], v32 offset:13312
	ds_read2_b32 v[150:151], v33 offset0:160 offset1:176
	ds_read_b128 v[108:111], v32 offset:12800
	ds_read_b128 v[124:127], v32 offset:13824
	ds_read_b128 v[112:115], v32 offset:13056
	s_waitcnt lgkmcnt(6)
	v_pk_mul_f32 v[156:157], v[54:55], v[100:101]
	v_pk_fma_f32 v[156:157], v[56:57], v[102:103], v[156:157]
	v_add_f32_e32 v2, v156, v157
	v_pk_mul_f32 v[8:9], v[54:55], v[72:73]
	v_pk_fma_f32 v[8:9], v[56:57], v[74:75], v[8:9]
	v_add_f32_dpp v2, v2, v2 row_ror:8 row_mask:0xf bank_mask:0xf bound_ctrl:1
	v_add_f32_e32 v17, v8, v9
	v_pk_mul_f32 v[4:5], v[96:97], v[148:149] op_sel:[0,1] op_sel_hi:[1,1]
	v_add_f32_dpp v2, v2, v2 row_ror:4 row_mask:0xf bank_mask:0xf bound_ctrl:1
	v_pk_mul_f32 v[6:7], v[98:99], v[148:149] op_sel:[0,1] op_sel_hi:[1,1]
	v_pk_fma_f32 v[4:5], v[54:55], v[88:89], v[4:5]
	v_add_f32_dpp v2, v2, v2 row_ror:2 row_mask:0xf bank_mask:0xf bound_ctrl:1
	v_pk_fma_f32 v[6:7], v[56:57], v[90:91], v[6:7]
	ds_read_b128 v[140:143], v32 offset:14848
	v_add_f32_dpp v2, v2, v2 row_ror:1 row_mask:0xf bank_mask:0xf bound_ctrl:1
	v_pk_fma_f32 v[54:55], v[104:105], v[2:3], v[4:5] op_sel_hi:[1,0,1] neg_lo:[1,0,0] neg_hi:[1,0,0]
	v_pk_fma_f32 v[56:57], v[106:107], v[2:3], v[6:7] op_sel_hi:[1,0,1] neg_lo:[1,0,0] neg_hi:[1,0,0]
	ds_read_b128 v[136:139], v32 offset:14592
	ds_read_b128 v[128:131], v32 offset:14080
	ds_read_b128 v[144:147], v32 offset:15104
	ds_read_b128 v[132:135], v32 offset:14336
	s_waitcnt lgkmcnt(5)
	v_pk_mul_f32 v[156:157], v[54:55], v[120:121]
	v_pk_fma_f32 v[156:157], v[56:57], v[122:123], v[156:157]
	v_add_f32_e32 v2, v156, v157
	v_pk_mul_f32 v[8:9], v[54:55], v[92:93]
	v_pk_fma_f32 v[8:9], v[56:57], v[94:95], v[8:9]
	v_add_f32_dpp v2, v2, v2 row_ror:8 row_mask:0xf bank_mask:0xf bound_ctrl:1
	v_add_f32_e32 v18, v8, v9
	v_pk_mul_f32 v[4:5], v[116:117], v[150:151] op_sel_hi:[1,0]
	v_add_f32_dpp v2, v2, v2 row_ror:4 row_mask:0xf bank_mask:0xf bound_ctrl:1
	v_pk_mul_f32 v[6:7], v[118:119], v[150:151] op_sel_hi:[1,0]
	v_pk_fma_f32 v[4:5], v[54:55], v[108:109], v[4:5]
	v_add_f32_dpp v2, v2, v2 row_ror:2 row_mask:0xf bank_mask:0xf bound_ctrl:1
	v_pk_fma_f32 v[6:7], v[56:57], v[110:111], v[6:7]
	ds_read_b128 v[80:83], v32 offset:16128
	v_add_f32_dpp v2, v2, v2 row_ror:1 row_mask:0xf bank_mask:0xf bound_ctrl:1
	v_pk_fma_f32 v[54:55], v[124:125], v[2:3], v[4:5] op_sel_hi:[1,0,1] neg_lo:[1,0,0] neg_hi:[1,0,0]
	v_pk_fma_f32 v[56:57], v[126:127], v[2:3], v[6:7] op_sel_hi:[1,0,1] neg_lo:[1,0,0] neg_hi:[1,0,0]
	ds_read_b128 v[76:79], v32 offset:15872
	ds_read2_b32 v[152:153], v33 offset0:192 offset1:208
	ds_read_b128 v[68:71], v32 offset:15360
	ds_read_b128 v[84:87], v32 offset:16384
	ds_read_b128 v[72:75], v32 offset:15616
	s_waitcnt lgkmcnt(6)
	v_pk_mul_f32 v[156:157], v[54:55], v[140:141]
	v_pk_fma_f32 v[156:157], v[56:57], v[142:143], v[156:157]
	v_add_f32_e32 v2, v156, v157
	v_pk_mul_f32 v[8:9], v[54:55], v[112:113]
	v_pk_fma_f32 v[8:9], v[56:57], v[114:115], v[8:9]
	v_add_f32_dpp v2, v2, v2 row_ror:8 row_mask:0xf bank_mask:0xf bound_ctrl:1
	v_add_f32_e32 v19, v8, v9
	v_pk_mul_f32 v[4:5], v[136:137], v[150:151] op_sel:[0,1] op_sel_hi:[1,1]
	v_add_f32_dpp v2, v2, v2 row_ror:4 row_mask:0xf bank_mask:0xf bound_ctrl:1
	v_pk_mul_f32 v[6:7], v[138:139], v[150:151] op_sel:[0,1] op_sel_hi:[1,1]
	v_pk_fma_f32 v[4:5], v[54:55], v[128:129], v[4:5]
	v_add_f32_dpp v2, v2, v2 row_ror:2 row_mask:0xf bank_mask:0xf bound_ctrl:1
	v_pk_fma_f32 v[6:7], v[56:57], v[130:131], v[6:7]
	ds_read_b128 v[100:103], v32 offset:17408
	v_add_f32_dpp v2, v2, v2 row_ror:1 row_mask:0xf bank_mask:0xf bound_ctrl:1
	v_pk_fma_f32 v[54:55], v[144:145], v[2:3], v[4:5] op_sel_hi:[1,0,1] neg_lo:[1,0,0] neg_hi:[1,0,0]
	v_pk_fma_f32 v[56:57], v[146:147], v[2:3], v[6:7] op_sel_hi:[1,0,1] neg_lo:[1,0,0] neg_hi:[1,0,0]
	ds_read_b128 v[96:99], v32 offset:17152
	ds_read_b128 v[88:91], v32 offset:16640
	ds_read_b128 v[104:107], v32 offset:17664
	ds_read_b128 v[92:95], v32 offset:16896
	s_waitcnt lgkmcnt(5)
	v_pk_mul_f32 v[156:157], v[54:55], v[80:81]
	v_pk_fma_f32 v[156:157], v[56:57], v[82:83], v[156:157]
	v_add_f32_e32 v2, v156, v157
	v_pk_mul_f32 v[8:9], v[54:55], v[132:133]
	v_pk_fma_f32 v[8:9], v[56:57], v[134:135], v[8:9]
	v_add_f32_dpp v2, v2, v2 row_ror:8 row_mask:0xf bank_mask:0xf bound_ctrl:1
	v_add_f32_e32 v20, v8, v9
	v_pk_mul_f32 v[4:5], v[76:77], v[152:153] op_sel_hi:[1,0]
	v_add_f32_dpp v2, v2, v2 row_ror:4 row_mask:0xf bank_mask:0xf bound_ctrl:1
	v_pk_mul_f32 v[6:7], v[78:79], v[152:153] op_sel_hi:[1,0]
	v_pk_fma_f32 v[4:5], v[54:55], v[68:69], v[4:5]
	v_add_f32_dpp v2, v2, v2 row_ror:2 row_mask:0xf bank_mask:0xf bound_ctrl:1
	v_pk_fma_f32 v[6:7], v[56:57], v[70:71], v[6:7]
	ds_read_b128 v[120:123], v32 offset:18688
	v_add_f32_dpp v2, v2, v2 row_ror:1 row_mask:0xf bank_mask:0xf bound_ctrl:1
	v_pk_fma_f32 v[54:55], v[84:85], v[2:3], v[4:5] op_sel_hi:[1,0,1] neg_lo:[1,0,0] neg_hi:[1,0,0]
	v_pk_fma_f32 v[56:57], v[86:87], v[2:3], v[6:7] op_sel_hi:[1,0,1] neg_lo:[1,0,0] neg_hi:[1,0,0]
	ds_read_b128 v[116:119], v32 offset:18432
	ds_read2_b32 v[154:155], v33 offset0:224 offset1:240
	ds_read_b128 v[108:111], v32 offset:17920
	ds_read_b128 v[124:127], v32 offset:18944
	ds_read_b128 v[112:115], v32 offset:18176
	s_waitcnt lgkmcnt(6)
	v_pk_mul_f32 v[156:157], v[54:55], v[100:101]
	v_pk_fma_f32 v[156:157], v[56:57], v[102:103], v[156:157]
	v_add_f32_e32 v2, v156, v157
	v_pk_mul_f32 v[8:9], v[54:55], v[72:73]
	v_pk_fma_f32 v[8:9], v[56:57], v[74:75], v[8:9]
	v_add_f32_dpp v2, v2, v2 row_ror:8 row_mask:0xf bank_mask:0xf bound_ctrl:1
	v_add_f32_e32 v21, v8, v9
	v_pk_mul_f32 v[4:5], v[96:97], v[152:153] op_sel:[0,1] op_sel_hi:[1,1]
	v_add_f32_dpp v2, v2, v2 row_ror:4 row_mask:0xf bank_mask:0xf bound_ctrl:1
	v_pk_mul_f32 v[6:7], v[98:99], v[152:153] op_sel:[0,1] op_sel_hi:[1,1]
	v_pk_fma_f32 v[4:5], v[54:55], v[88:89], v[4:5]
	v_add_f32_dpp v2, v2, v2 row_ror:2 row_mask:0xf bank_mask:0xf bound_ctrl:1
	v_pk_fma_f32 v[6:7], v[56:57], v[90:91], v[6:7]
	ds_read_b128 v[140:143], v32 offset:19968
	v_add_f32_dpp v2, v2, v2 row_ror:1 row_mask:0xf bank_mask:0xf bound_ctrl:1
	v_pk_fma_f32 v[54:55], v[104:105], v[2:3], v[4:5] op_sel_hi:[1,0,1] neg_lo:[1,0,0] neg_hi:[1,0,0]
	v_pk_fma_f32 v[56:57], v[106:107], v[2:3], v[6:7] op_sel_hi:[1,0,1] neg_lo:[1,0,0] neg_hi:[1,0,0]
	ds_read_b128 v[136:139], v32 offset:19712
	ds_read_b128 v[128:131], v32 offset:19200
	ds_read_b128 v[144:147], v32 offset:20224
	ds_read_b128 v[132:135], v32 offset:19456
	s_waitcnt lgkmcnt(5)
	s_add_i32 s13, s36, s83
	s_add_i32 s13, s13, 1
	s_and_b32 s13, s13, 3
	s_lshl_b32 s12, s13, 2
	s_add_i32 s12, s12, 0x15000
	s_mul_i32 s13, s13, 0x5400
	v_mov_b32_e32 v26, s12
	v_add_u32_e32 v34, s13, v183
	v_add_u32_e32 v35, s13, v184
	v_add_u32_e32 v35, 0x5000, v35
	v_pk_mul_f32 v[156:157], v[54:55], v[120:121]
	v_pk_fma_f32 v[156:157], v[56:57], v[122:123], v[156:157]
	v_add_f32_e32 v2, v156, v157
	v_pk_mul_f32 v[8:9], v[54:55], v[92:93]
	v_pk_fma_f32 v[8:9], v[56:57], v[94:95], v[8:9]
	v_add_f32_dpp v2, v2, v2 row_ror:8 row_mask:0xf bank_mask:0xf bound_ctrl:1
	v_add_f32_e32 v22, v8, v9
	v_pk_mul_f32 v[4:5], v[116:117], v[154:155] op_sel_hi:[1,0]
	v_add_f32_dpp v2, v2, v2 row_ror:4 row_mask:0xf bank_mask:0xf bound_ctrl:1
	v_pk_mul_f32 v[6:7], v[118:119], v[154:155] op_sel_hi:[1,0]
	v_pk_fma_f32 v[4:5], v[54:55], v[108:109], v[4:5]
	v_add_f32_dpp v2, v2, v2 row_ror:2 row_mask:0xf bank_mask:0xf bound_ctrl:1
	v_pk_fma_f32 v[6:7], v[56:57], v[110:111], v[6:7]
	ds_read_b32 v25, v26
	v_add_f32_dpp v2, v2, v2 row_ror:1 row_mask:0xf bank_mask:0xf bound_ctrl:1
	v_pk_fma_f32 v[54:55], v[124:125], v[2:3], v[4:5] op_sel_hi:[1,0,1] neg_lo:[1,0,0] neg_hi:[1,0,0]
	v_pk_fma_f32 v[56:57], v[126:127], v[2:3], v[6:7] op_sel_hi:[1,0,1] neg_lo:[1,0,0] neg_hi:[1,0,0]
	ds_read_b128 v[80:83], v34 offset:768
	ds_read_b128 v[76:79], v34 offset:512
	ds_read2_b32 v[148:149], v35 offset0:0 offset1:16
	ds_read_b128 v[68:71], v34 offset:0
	ds_read_b128 v[84:87], v34 offset:1024
	ds_read_b128 v[72:75], v34 offset:256
	s_waitcnt lgkmcnt(7)
	v_pk_mul_f32 v[156:157], v[54:55], v[140:141]
	v_pk_fma_f32 v[156:157], v[56:57], v[142:143], v[156:157]
	v_add_f32_e32 v2, v156, v157
	v_pk_mul_f32 v[8:9], v[54:55], v[112:113]
	v_pk_fma_f32 v[8:9], v[56:57], v[114:115], v[8:9]
	v_add_f32_dpp v2, v2, v2 row_ror:8 row_mask:0xf bank_mask:0xf bound_ctrl:1
	v_add_f32_e32 v23, v8, v9
	v_pk_mul_f32 v[4:5], v[136:137], v[154:155] op_sel:[0,1] op_sel_hi:[1,1]
	v_add_f32_dpp v2, v2, v2 row_ror:4 row_mask:0xf bank_mask:0xf bound_ctrl:1
	v_pk_mul_f32 v[6:7], v[138:139], v[154:155] op_sel:[0,1] op_sel_hi:[1,1]
	v_pk_fma_f32 v[4:5], v[54:55], v[128:129], v[4:5]
	v_add_f32_dpp v2, v2, v2 row_ror:2 row_mask:0xf bank_mask:0xf bound_ctrl:1
	v_pk_fma_f32 v[6:7], v[56:57], v[130:131], v[6:7]
	ds_read_b128 v[100:103], v34 offset:2048
	v_add_f32_dpp v2, v2, v2 row_ror:1 row_mask:0xf bank_mask:0xf bound_ctrl:1
	v_pk_fma_f32 v[54:55], v[144:145], v[2:3], v[4:5] op_sel_hi:[1,0,1] neg_lo:[1,0,0] neg_hi:[1,0,0]
	v_pk_fma_f32 v[56:57], v[146:147], v[2:3], v[6:7] op_sel_hi:[1,0,1] neg_lo:[1,0,0] neg_hi:[1,0,0]
	ds_read_b128 v[96:99], v34 offset:1792
	ds_read_b128 v[88:91], v34 offset:1280
	ds_read_b128 v[104:107], v34 offset:2304
	ds_read_b128 v[92:95], v34 offset:1536
	v_pk_mul_f32 v[8:9], v[54:55], v[132:133]
	v_pk_fma_f32 v[8:9], v[56:57], v[134:135], v[8:9]
	v_add_f32_e32 v24, v8, v9
	v_add_f32_dpp v66, v66, v66 row_ror:8 row_mask:0xf bank_mask:0x3
	v_add_f32_dpp v66, v17, v17 row_ror:8 row_mask:0xf bank_mask:0xc
	v_add_f32_dpp v10, v10, v10 row_ror:8 row_mask:0xf bank_mask:0x3
	v_add_f32_dpp v10, v18, v18 row_ror:8 row_mask:0xf bank_mask:0xc
	v_add_f32_dpp v11, v11, v11 row_ror:8 row_mask:0xf bank_mask:0x3
	v_add_f32_dpp v11, v19, v19 row_ror:8 row_mask:0xf bank_mask:0xc
	v_add_f32_dpp v12, v12, v12 row_ror:8 row_mask:0xf bank_mask:0x3
	v_add_f32_dpp v12, v20, v20 row_ror:8 row_mask:0xf bank_mask:0xc
	v_add_f32_dpp v13, v13, v13 row_ror:8 row_mask:0xf bank_mask:0x3
	v_add_f32_dpp v13, v21, v21 row_ror:8 row_mask:0xf bank_mask:0xc
	v_add_f32_dpp v14, v14, v14 row_ror:8 row_mask:0xf bank_mask:0x3
	v_add_f32_dpp v14, v22, v22 row_ror:8 row_mask:0xf bank_mask:0xc
	v_add_f32_dpp v15, v15, v15 row_ror:8 row_mask:0xf bank_mask:0x3
	v_add_f32_dpp v15, v23, v23 row_ror:8 row_mask:0xf bank_mask:0xc
	v_add_f32_dpp v16, v16, v16 row_ror:8 row_mask:0xf bank_mask:0x3
	v_add_f32_dpp v16, v24, v24 row_ror:8 row_mask:0xf bank_mask:0xc
	v_add_f32_dpp v66, v66, v66 row_shl:4 row_mask:0xf bank_mask:0x5
	v_add_f32_dpp v66, v13, v13 row_shr:4 row_mask:0xf bank_mask:0xa
	v_add_f32_dpp v10, v10, v10 row_shl:4 row_mask:0xf bank_mask:0x5
	v_add_f32_dpp v10, v14, v14 row_shr:4 row_mask:0xf bank_mask:0xa
	v_add_f32_dpp v11, v11, v11 row_shl:4 row_mask:0xf bank_mask:0x5
	v_add_f32_dpp v11, v15, v15 row_shr:4 row_mask:0xf bank_mask:0xa
	v_add_f32_dpp v12, v12, v12 row_shl:4 row_mask:0xf bank_mask:0x5
	v_add_f32_dpp v12, v16, v16 row_shr:4 row_mask:0xf bank_mask:0xa
	v_add_f32_dpp v27, v66, v66 quad_perm:[2,3,0,1] row_mask:0xf bank_mask:0xf
	v_add_f32_dpp v28, v11, v11 quad_perm:[2,3,0,1] row_mask:0xf bank_mask:0xf
	v_cndmask_b32_e64 v66, v27, v28, s[78:79]
	v_add_f32_dpp v27, v10, v10 quad_perm:[2,3,0,1] row_mask:0xf bank_mask:0xf
	v_add_f32_dpp v28, v12, v12 quad_perm:[2,3,0,1] row_mask:0xf bank_mask:0xf
	v_cndmask_b32_e64 v10, v27, v28, s[78:79]
	s_add_i32 s13, s86, 0x15010
	v_mov_b32_e32 v26, s13
	s_mov_b64 s[12:13], exec
	s_mov_b64 exec, s[38:39]
	ds_add_u32 v26, v203
	s_mov_b64 exec, s[12:13]
	v_add_f32_dpp v27, v10, v10 quad_perm:[1,0,3,2] row_mask:0xf bank_mask:0xf
	v_add_f32_dpp v28, v66, v66 quad_perm:[1,0,3,2] row_mask:0xf bank_mask:0xf
	v_cndmask_b32_e64 v66, v28, v27, s[96:97]
	v_lshl_add_u32 v64, s36, 4, v59
	v_ashrrev_i32_e32 v65, 31, v64
	v_lshlrev_b64 v[64:65], 12, v[64:65]
	s_add_i32 s36, s36, 1
	v_lshl_add_u64 v[64:65], v[62:63], 0, v[64:65]
	s_cmpk_gt_u32 s84, 0xff
	s_cbranch_scc1 .Lsc_nopub
	s_waitcnt vmcnt(0)
	s_add_i32 s12, s36, -1
	v_mov_b32_e32 v30, s12
	s_mov_b64 s[12:13], exec
	s_mov_b64 exec, s[38:39]
	global_store_dword v29, v30, s[98:99]
	s_mov_b64 exec, s[12:13]
.Lsc_nopub:
	global_store_dword v[64:65], v66, off
	s_cmp_eq_u32 s36, s85
	s_cbranch_scc1 .Lsc_exit
	s_add_i32 s77, s36, s83
	s_and_b32 s86, s77, 3
	s_lshl_b32 s86, s86, 2
	s_add_i32 s77, s77, 1
	v_mov_b32_e32 v32, v34
	v_mov_b32_e32 v33, v35
	s_waitcnt lgkmcnt(12)
	v_cmp_le_u32_e32 vcc, s77, v25
	s_cbranch_vccnz .Lsc_chunk
	s_branch .Lsc_pollentry
.Lsc_exit:
	s_waitcnt lgkmcnt(0)
	s_cmpk_gt_u32 s84, 0xff
	s_cbranch_scc1 .Lsc_nopub2
	s_waitcnt vmcnt(0)
	v_mov_b32_e32 v30, s85
	s_mov_b64 s[12:13], exec
	s_mov_b64 exec, s[38:39]
	global_store_dword v29, v30, s[98:99]
	s_mov_b64 exec, s[12:13]
.Lsc_nopub2:
.LBB0_477:
	v_lshl_add_u64 v[60:61], v[60:61], 2, s[0:1]
	v_mov_b32_e32 v59, v1
	v_lshl_add_u64 v[58:59], v[60:61], 0, v[58:59]
	s_mov_b64 s[12:13], 0
	global_store_dwordx4 v[58:59], v[54:57], off

.Lpost_check:
	v_readfirstlane_b32 s0, v159
	s_lshr_b32 s0, s0, 6
	s_cmp_lt_u32 s0, 5
	s_cbranch_scc1 .LBB0_552
	s_mov_b64 exec, -1
	s_sub_u32 s12, s0, 5
	v_mov_b32_e32 v2, 0x15030
	ds_read_b32 v2, v2
	s_waitcnt lgkmcnt(0)
	v_readfirstlane_b32 s0, v2
	v_mbcnt_lo_u32_b32 v2, -1, 0
	v_mbcnt_hi_u32_b32 v2, -1, v2
	s_and_b32 s13, s0, 3
	s_lshr_b32 s36, s0, 2
	s_and_b32 s38, s36, 15
	s_lshr_b32 s39, s36, 4
	s_add_u32 s40, s24, 0xbb97000
	s_addc_u32 s41, s25, 0
	s_add_u32 s42, s24, 0x152b7000
	s_addc_u32 s43, s25, 0
	s_add_u32 s44, s24, 0x172f7000
	s_addc_u32 s45, s25, 0
	s_add_u32 s46, s24, 0x4f90000
	s_addc_u32 s47, s25, 0
	s_add_u32 s48, s24, 0x5017000
	s_addc_u32 s49, s25, 0
	s_add_u32 s50, s24, 0x4a80000
	s_addc_u32 s51, s25, 0
	s_lshl_b32 s0, s36, 6
	s_add_u32 s50, s50, s0
	s_addc_u32 s51, s51, 0
	v_readlane_b32 s52, v254, 49
	v_readlane_b32 s53, v254, 50
	v_readlane_b32 s54, v254, 51
	v_readlane_b32 s55, v254, 52
	s_lshl_b32 s0, s38, 8
	s_add_u32 s52, s52, s0
	s_addc_u32 s53, s53, 0
	s_add_u32 s54, s54, s0
	s_addc_u32 s55, s55, 0
	s_mov_b32 s58, 0x3c800000
	v_lshlrev_b32_e32 v3, 2, v2
	v_lshrrev_b32_e32 v5, 3, v2
	v_and_b32_e32 v6, 7, v2
	v_lshlrev_b32_e32 v7, 5, v6
	global_load_dwordx4 v[8:11], v7, s[52:53]
	global_load_dwordx4 v[12:15], v7, s[52:53] offset:16
	global_load_dwordx4 v[16:19], v7, s[54:55]
	global_load_dwordx4 v[20:23], v7, s[54:55] offset:16
	s_lshl_b32 s0, s38, 8
	v_add_u32_e32 v24, s0, v7
	s_lshl_b32 s0, s38, 7
	v_lshl_add_u32 v25, v6, 4, s0
	s_lshl_b32 s1, s38, 2
	v_mov_b32_e32 v26, s1
	v_add_u32_e32 v27, 0x800, v25
	s_mov_b32 s59, s12
	s_mov_b32 s64, 0
.Lpost_loop:
	s_lshl_b32 s62, s59, 2
	s_add_i32 s62, s62, s13
	s_add_i32 s63, s62, 1
	v_mov_b32_e32 v28, s63
	s_cmp_ge_u32 s64, s63
	s_cbranch_scc1 .Lpost_go
.Lpost_poll:
	global_load_dword v4, v3, s[50:51] sc1
	s_waitcnt vmcnt(0)
	s_nop 0
	v_min_u32_dpp v4, v4, v4 row_ror:8 row_mask:0xf bank_mask:0xf
	s_nop 1
	v_min_u32_dpp v4, v4, v4 row_ror:4 row_mask:0xf bank_mask:0xf
	s_nop 1
	v_min_u32_dpp v4, v4, v4 row_ror:2 row_mask:0xf bank_mask:0xf
	s_nop 1
	v_min_u32_dpp v4, v4, v4 row_ror:1 row_mask:0xf bank_mask:0xf
	s_nop 0
	v_readfirstlane_b32 s64, v4
	s_cmp_ge_u32 s64, s63
	s_cbranch_scc1 .Lpost_go
	s_sleep 8
	s_branch .Lpost_poll
.Lpost_go:
	s_lshl_b32 s0, s39, 11
	s_lshl_b32 s1, s62, 4
	s_add_i32 s0, s0, s1
	v_add_u32_e32 v29, s0, v5
	v_lshl_add_u32 v47, v29, 12, v24
	v_lshl_add_u32 v48, v29, 11, v25
	v_lshl_add_u32 v49, v29, 6, v26
	v_lshl_add_u32 v50, v29, 12, v27
	global_load_dwordx4 v[30:33], v47, s[40:41] sc1
	global_load_dwordx4 v[34:37], v47, s[40:41] offset:16 sc1
	global_load_dwordx4 v[38:41], v48, s[42:43]
	global_load_dwordx4 v[42:45], v48, s[44:45]
	global_load_dword v46, v49, s[46:47]
	v_add_u32_e32 v87, 0x8000, v47
	v_add_u32_e32 v88, 0x4000, v48
	v_add_u32_e32 v89, 0x200, v49
	v_add_u32_e32 v90, 0x8000, v50
	global_load_dwordx4 v[70:73], v87, s[40:41] sc1
	global_load_dwordx4 v[74:77], v87, s[40:41] offset:16 sc1
	global_load_dwordx4 v[78:81], v88, s[42:43]
	global_load_dwordx4 v[82:85], v88, s[44:45]
	global_load_dword v86, v89, s[46:47]
	s_waitcnt vmcnt(5)
	v_add_f32_e32 v51, v30, v31
	v_add_f32_e32 v51, v32, v51
	v_add_f32_e32 v51, v33, v51
	v_add_f32_e32 v51, v34, v51
	v_add_f32_e32 v51, v35, v51
	v_add_f32_e32 v51, v36, v51
	v_add_f32_e32 v51, v37, v51
	s_nop 1
	v_add_f32_dpp v51, v51, v51 quad_perm:[1,0,3,2] row_mask:0xf bank_mask:0xf
	s_nop 1
	v_add_f32_dpp v51, v51, v51 quad_perm:[2,3,0,1] row_mask:0xf bank_mask:0xf
	s_nop 1
	v_add_f32_dpp v51, v51, v51 row_half_mirror row_mask:0xf bank_mask:0xf
	v_mul_f32_e32 v52, s58, v51
	v_sub_f32_e32 v30, v30, v52
	v_sub_f32_e32 v31, v31, v52
	v_sub_f32_e32 v32, v32, v52
	v_sub_f32_e32 v33, v33, v52
	v_sub_f32_e32 v34, v34, v52
	v_sub_f32_e32 v35, v35, v52
	v_sub_f32_e32 v36, v36, v52
	v_sub_f32_e32 v37, v37, v52
	v_mul_f32_e32 v62, v30, v30
	v_mul_f32_e32 v53, v31, v31
	v_add_f32_e32 v62, v53, v62
	v_mul_f32_e32 v53, v32, v32
	v_add_f32_e32 v62, v53, v62
	v_mul_f32_e32 v53, v33, v33
	v_add_f32_e32 v62, v53, v62
	v_mul_f32_e32 v53, v34, v34
	v_add_f32_e32 v62, v53, v62
	v_mul_f32_e32 v53, v35, v35
	v_add_f32_e32 v62, v53, v62
	v_mul_f32_e32 v53, v36, v36
	v_add_f32_e32 v62, v53, v62
	v_mul_f32_e32 v53, v37, v37
	v_add_f32_e32 v62, v53, v62
	s_nop 1
	v_add_f32_dpp v62, v62, v62 quad_perm:[1,0,3,2] row_mask:0xf bank_mask:0xf
	s_nop 1
	v_add_f32_dpp v62, v62, v62 quad_perm:[2,3,0,1] row_mask:0xf bank_mask:0xf
	s_nop 1
	v_add_f32_dpp v62, v62, v62 row_half_mirror row_mask:0xf bank_mask:0xf
	v_fma_f32 v62, v62, s58, v162
	v_mul_f32_e32 v53, 0x4b800000, v62
	v_cmp_gt_f32_e32 vcc, s5, v62
	s_nop 1
	v_cndmask_b32_e32 v53, v62, v53, vcc
	v_rsq_f32_e32 v53, v53
	s_nop 0
	v_mul_f32_e32 v52, 0x45800000, v53
	v_cndmask_b32_e32 v52, v53, v52, vcc
	v_mul_f32_e32 v30, v30, v52
	v_fma_f32 v30, v8, v30, v16
	v_lshlrev_b32_e32 v53, 16, v38
	v_fma_f32 v30, v46, v53, v30
	v_lshlrev_b32_e32 v53, 16, v42
	v_mul_f32_e32 v30, v30, v53
	v_mul_f32_e32 v31, v31, v52
	v_fma_f32 v31, v9, v31, v17
	v_and_b32_e32 v53, 0xffff0000, v38
	v_fma_f32 v31, v46, v53, v31
	v_and_b32_e32 v53, 0xffff0000, v42
	v_mul_f32_e32 v31, v31, v53
	v_mul_f32_e32 v32, v32, v52
	v_fma_f32 v32, v10, v32, v18
	v_lshlrev_b32_e32 v53, 16, v39
	v_fma_f32 v32, v46, v53, v32
	v_lshlrev_b32_e32 v53, 16, v43
	v_mul_f32_e32 v32, v32, v53
	v_mul_f32_e32 v33, v33, v52
	v_fma_f32 v33, v11, v33, v19
	v_and_b32_e32 v53, 0xffff0000, v39
	v_fma_f32 v33, v46, v53, v33
	v_and_b32_e32 v53, 0xffff0000, v43
	v_mul_f32_e32 v33, v33, v53
	v_mul_f32_e32 v34, v34, v52
	v_fma_f32 v34, v12, v34, v20
	v_lshlrev_b32_e32 v53, 16, v40
	v_fma_f32 v34, v46, v53, v34
	v_lshlrev_b32_e32 v53, 16, v44
	v_mul_f32_e32 v34, v34, v53
	v_mul_f32_e32 v35, v35, v52
	v_fma_f32 v35, v13, v35, v21
	v_and_b32_e32 v53, 0xffff0000, v40
	v_fma_f32 v35, v46, v53, v35
	v_and_b32_e32 v53, 0xffff0000, v44
	v_mul_f32_e32 v35, v35, v53
	v_mul_f32_e32 v36, v36, v52
	v_fma_f32 v36, v14, v36, v22
	v_lshlrev_b32_e32 v53, 16, v41
	v_fma_f32 v36, v46, v53, v36
	v_lshlrev_b32_e32 v53, 16, v45
	v_mul_f32_e32 v36, v36, v53
	v_mul_f32_e32 v37, v37, v52
	v_fma_f32 v37, v15, v37, v23
	v_and_b32_e32 v53, 0xffff0000, v41
	v_fma_f32 v37, v46, v53, v37
	v_and_b32_e32 v53, 0xffff0000, v45
	v_mul_f32_e32 v37, v37, v53
	v_cvt_pk_bf16_f32 v54, v30, v31
	v_cvt_pk_bf16_f32 v55, v32, v33
	v_cvt_pk_bf16_f32 v56, v34, v35
	v_cvt_pk_bf16_f32 v57, v36, v37
	global_store_dwordx4 v50, v[54:57], s[48:49]
	s_waitcnt vmcnt(0)
	v_add_f32_e32 v91, v70, v71
	v_add_f32_e32 v91, v72, v91
	v_add_f32_e32 v91, v73, v91
	v_add_f32_e32 v91, v74, v91
	v_add_f32_e32 v91, v75, v91
	v_add_f32_e32 v91, v76, v91
	v_add_f32_e32 v91, v77, v91
	s_nop 1
	v_add_f32_dpp v91, v91, v91 quad_perm:[1,0,3,2] row_mask:0xf bank_mask:0xf
	s_nop 1
	v_add_f32_dpp v91, v91, v91 quad_perm:[2,3,0,1] row_mask:0xf bank_mask:0xf
	s_nop 1
	v_add_f32_dpp v91, v91, v91 row_half_mirror row_mask:0xf bank_mask:0xf
	v_mul_f32_e32 v92, s58, v91
	v_sub_f32_e32 v70, v70, v92
	v_sub_f32_e32 v71, v71, v92
	v_sub_f32_e32 v72, v72, v92
	v_sub_f32_e32 v73, v73, v92
	v_sub_f32_e32 v74, v74, v92
	v_sub_f32_e32 v75, v75, v92
	v_sub_f32_e32 v76, v76, v92
	v_sub_f32_e32 v77, v77, v92
	v_mul_f32_e32 v102, v70, v70
	v_mul_f32_e32 v93, v71, v71
	v_add_f32_e32 v102, v93, v102
	v_mul_f32_e32 v93, v72, v72
	v_add_f32_e32 v102, v93, v102
	v_mul_f32_e32 v93, v73, v73
	v_add_f32_e32 v102, v93, v102
	v_mul_f32_e32 v93, v74, v74
	v_add_f32_e32 v102, v93, v102
	v_mul_f32_e32 v93, v75, v75
	v_add_f32_e32 v102, v93, v102
	v_mul_f32_e32 v93, v76, v76
	v_add_f32_e32 v102, v93, v102
	v_mul_f32_e32 v93, v77, v77
	v_add_f32_e32 v102, v93, v102
	s_nop 1
	v_add_f32_dpp v102, v102, v102 quad_perm:[1,0,3,2] row_mask:0xf bank_mask:0xf
	s_nop 1
	v_add_f32_dpp v102, v102, v102 quad_perm:[2,3,0,1] row_mask:0xf bank_mask:0xf
	s_nop 1
	v_add_f32_dpp v102, v102, v102 row_half_mirror row_mask:0xf bank_mask:0xf
	v_fma_f32 v102, v102, s58, v162
	v_mul_f32_e32 v93, 0x4b800000, v102
	v_cmp_gt_f32_e32 vcc, s5, v102
	s_nop 1
	v_cndmask_b32_e32 v93, v102, v93, vcc
	v_rsq_f32_e32 v93, v93
	s_nop 0
	v_mul_f32_e32 v92, 0x45800000, v93
	v_cndmask_b32_e32 v92, v93, v92, vcc
	v_mul_f32_e32 v70, v70, v92
	v_fma_f32 v70, v8, v70, v16
	v_lshlrev_b32_e32 v93, 16, v78
	v_fma_f32 v70, v86, v93, v70
	v_lshlrev_b32_e32 v93, 16, v82
	v_mul_f32_e32 v70, v70, v93
	v_mul_f32_e32 v71, v71, v92
	v_fma_f32 v71, v9, v71, v17
	v_and_b32_e32 v93, 0xffff0000, v78
	v_fma_f32 v71, v86, v93, v71
	v_and_b32_e32 v93, 0xffff0000, v82
	v_mul_f32_e32 v71, v71, v93
	v_mul_f32_e32 v72, v72, v92
	v_fma_f32 v72, v10, v72, v18
	v_lshlrev_b32_e32 v93, 16, v79
	v_fma_f32 v72, v86, v93, v72
	v_lshlrev_b32_e32 v93, 16, v83
	v_mul_f32_e32 v72, v72, v93
	v_mul_f32_e32 v73, v73, v92
	v_fma_f32 v73, v11, v73, v19
	v_and_b32_e32 v93, 0xffff0000, v79
	v_fma_f32 v73, v86, v93, v73
	v_and_b32_e32 v93, 0xffff0000, v83
	v_mul_f32_e32 v73, v73, v93
	v_mul_f32_e32 v74, v74, v92
	v_fma_f32 v74, v12, v74, v20
	v_lshlrev_b32_e32 v93, 16, v80
	v_fma_f32 v74, v86, v93, v74
	v_lshlrev_b32_e32 v93, 16, v84
	v_mul_f32_e32 v74, v74, v93
	v_mul_f32_e32 v75, v75, v92
	v_fma_f32 v75, v13, v75, v21
	v_and_b32_e32 v93, 0xffff0000, v80
	v_fma_f32 v75, v86, v93, v75
	v_and_b32_e32 v93, 0xffff0000, v84
	v_mul_f32_e32 v75, v75, v93
	v_mul_f32_e32 v76, v76, v92
	v_fma_f32 v76, v14, v76, v22
	v_lshlrev_b32_e32 v93, 16, v81
	v_fma_f32 v76, v86, v93, v76
	v_lshlrev_b32_e32 v93, 16, v85
	v_mul_f32_e32 v76, v76, v93
	v_mul_f32_e32 v77, v77, v92
	v_fma_f32 v77, v15, v77, v23
	v_and_b32_e32 v93, 0xffff0000, v81
	v_fma_f32 v77, v86, v93, v77
	v_and_b32_e32 v93, 0xffff0000, v85
	v_mul_f32_e32 v77, v77, v93
	v_cvt_pk_bf16_f32 v94, v70, v71
	v_cvt_pk_bf16_f32 v95, v72, v73
	v_cvt_pk_bf16_f32 v96, v74, v75
	v_cvt_pk_bf16_f32 v97, v76, v77
	global_store_dwordx4 v90, v[94:97], s[48:49]
	s_add_i32 s59, s59, 3
	s_cmp_lt_u32 s59, 32
	s_cbranch_scc1 .Lpost_loop
	s_waitcnt vmcnt(0)
	s_branch .LBB0_552

.LBB0_556:
	s_or_b64 exec, exec, s[0:1]
	v_cmp_gt_u32_e32 vcc, 4, v166
	s_and_saveexec_b64 s[0:1], vcc
	v_readlane_b32 s12, v255, 13
	s_add_u32 s38, s24, 0x4a80000
	s_addc_u32 s39, s25, 0
	s_lshl_b32 s12, s12, 4
	v_lshl_add_u32 v2, v166, 2, s12
	global_store_dword v2, v1, s[38:39]
	s_or_b64 exec, exec, s[0:1]
	v_readlane_b32 s0, v250, 4
	v_readlane_b32 s1, v250, 5
	s_andn2_b64 vcc, exec, s[0:1]
	s_mov_b32 s66, 0x3d000
	s_movk_i32 s67, 0x207f
	s_movk_i32 s68, 0x7f
	s_cbranch_vccnz .LBB0_583
	v_readlane_b32 s0, v250, 46
	v_readlane_b32 s1, v250, 47
	s_andn2_b64 vcc, exec, s[0:1]
	v_readfirstlane_b32 s52, v166
	s_cbranch_vccnz .LBB0_582
	v_readlane_b32 s12, v250, 48
	v_readlane_b32 s13, v250, 49
	v_readlane_b32 s38, v254, 20
	v_readlane_b32 s46, v250, 52
	s_mov_b64 s[0:1], 0x6917000
	s_mov_b32 s62, 1
	s_andn2_b64 vcc, exec, s[12:13]
	v_readlane_b32 s39, v254, 21
	s_mov_b32 s61, s38
	v_readlane_b32 s58, v250, 51
	v_readlane_b32 s47, v250, 53
	s_cbranch_vccnz .LBB0_560
	v_readlane_b32 s38, v253, 32
	v_readlane_b32 s12, v253, 28
	v_readlane_b32 s46, v253, 30
	s_mov_b64 s[0:1], 0x5017000
	s_mov_b32 s62, 0
	v_readlane_b32 s39, v253, 33
	s_mov_b32 s61, s38
	s_mov_b32 s58, s12
	v_readlane_b32 s47, v253, 31
	v_readlane_b32 s13, v253, 29
